# conv-tile epilogues: s_nop 1 before v_mov_b32_dpp dropped where the source is not written by the two preceding instructions (76 of 80)
# baseline (speedup 1.0000x reference)
.LBB0_282:
	s_ashr_i32 s77, s76, 31
	s_lshl_b64 s[10:11], s[76:77], 21
	v_ashrrev_i32_e32 v168, 5, v152
	s_add_u32 s10, s93, s10
	v_ashrrev_i32_e32 v169, 31, v168
	s_addc_u32 s11, s94, s11
	v_lshlrev_b64 v[168:169], 14, v[168:169]
	v_and_b32_e32 v152, 28, v166
	v_lshl_add_u64 v[168:169], s[10:11], 0, v[168:169]
	v_lshlrev_b32_e32 v152, 1, v152
	v_lshl_add_u64 v[168:169], v[168:169], 0, v[152:153]
	s_mov_b64 s[12:13], 0x80000
	v_lshl_add_u64 v[168:169], v[168:169], 0, s[12:13]
	s_lshl_b64 s[12:13], s[60:61], 16
	s_add_u32 s9, s10, s12
	s_addc_u32 s11, s11, s13
	v_lshlrev_b32_e32 v152, 4, v186
	s_add_u32 s10, s9, s42
	v_lshl_add_u32 v170, v185, 8, v152
	s_addc_u32 s11, s11, s43
	v_ashrrev_i32_e32 v171, 31, v170
	s_and_b32 s60, s8, 12
	v_cmp_lt_i32_e64 s[8:9], 0, v186
	v_pk_mul_f32 v[174:175], v[120:121], v[116:117]
	v_lshl_add_u64 v[170:171], s[10:11], 0, v[170:171]
	v_cmp_lt_i32_e64 s[10:11], 1, v186
	s_waitcnt lgkmcnt(0)
	v_mov_b32_dpp v152, v140 row_ror:1 row_mask:0xf bank_mask:0xf
	v_mov_b32_dpp v140, v140 row_ror:2 row_mask:0xf bank_mask:0xf
	v_mov_b32_dpp v163, v141 row_ror:1 row_mask:0xf bank_mask:0xf
	v_mov_b32_dpp v187, v141 row_ror:2 row_mask:0xf bank_mask:0xf
	v_mov_b32_dpp v194, v142 row_ror:1 row_mask:0xf bank_mask:0xf
	v_mov_b32_dpp v142, v142 row_ror:2 row_mask:0xf bank_mask:0xf
	v_mov_b32_dpp v195, v143 row_ror:1 row_mask:0xf bank_mask:0xf
	v_mov_b32_dpp v196, v143 row_ror:2 row_mask:0xf bank_mask:0xf
	v_mov_b32_dpp v141, v174 row_ror:1 row_mask:0xf bank_mask:0xf
	v_mov_b32_e32 v192, v174
	v_cndmask_b32_e64 v189, v152, v141, s[8:9]
	s_waitcnt vmcnt(1)
	v_mov_b32_e32 v193, v132
	s_waitcnt vmcnt(0)
	v_mov_b32_e32 v188, v136
	v_mov_b32_dpp v143, v174 row_ror:2 row_mask:0xf bank_mask:0xf
	v_pk_mul_f32 v[188:189], v[192:193], v[188:189]
	v_cndmask_b32_e64 v140, v140, v143, s[10:11]
	v_fma_f32 v140, v128, v140, v189
	v_add_f32_e32 v197, v188, v140
	v_mov_b32_dpp v152, v175 row_ror:1 row_mask:0xf bank_mask:0xf
	v_mov_b32_e32 v192, v175
	v_cndmask_b32_e64 v189, v163, v152, s[8:9]
	v_mov_b32_e32 v193, v133
	v_mov_b32_e32 v188, v137
	v_mov_b32_dpp v174, v175 row_ror:2 row_mask:0xf bank_mask:0xf
	v_pk_mul_f32 v[188:189], v[192:193], v[188:189]
	v_cndmask_b32_e64 v163, v187, v174, s[10:11]
	v_pk_mul_f32 v[190:191], v[122:123], v[118:119]
	v_mov_b32_e32 v140, v137
	v_fma_f32 v137, v129, v163, v189
	v_add_f32_e32 v137, v188, v137
	v_mov_b32_dpp v175, v190 row_ror:1 row_mask:0xf bank_mask:0xf
	v_mov_b32_e32 v192, v190
	v_cndmask_b32_e64 v189, v194, v175, s[8:9]
	v_mov_b32_e32 v193, v134
	v_mov_b32_e32 v188, v138
	v_mov_b32_dpp v187, v190 row_ror:2 row_mask:0xf bank_mask:0xf
	v_pk_mul_f32 v[188:189], v[192:193], v[188:189]
	v_cndmask_b32_e64 v142, v142, v187, s[10:11]
	v_fma_f32 v142, v130, v142, v189
	v_add_f32_e32 v163, v188, v142
	v_mov_b32_dpp v188, v191 row_ror:1 row_mask:0xf bank_mask:0xf
	v_mov_b32_dpp v189, v191 row_ror:2 row_mask:0xf bank_mask:0xf
	v_mov_b32_e32 v190, v191
	v_cndmask_b32_e64 v193, v195, v188, s[8:9]
	v_mov_b32_e32 v191, v135
	v_mov_b32_e32 v192, v139
	v_cndmask_b32_e64 v194, v196, v189, s[10:11]
	v_pk_mul_f32 v[190:191], v[190:191], v[192:193]
	v_mov_b32_e32 v142, v139
	v_fma_f32 v139, v131, v194, v191
	v_add_f32_e32 v139, v190, v139
	v_mul_f32_e32 v190, v124, v197
	v_mul_f32_e32 v137, v125, v137
	v_cvt_pk_bf16_f32 v190, v190, v137
	v_mul_f32_e32 v137, v126, v163
	v_mul_f32_e32 v139, v127, v139
	v_cvt_pk_bf16_f32 v191, v137, v139
	v_mul_f32_e32 v137, 0xbfb8aa3b, v112
	v_mul_f32_e32 v139, 0xbfb8aa3b, v113
	v_exp_f32_e32 v137, v137
	v_exp_f32_e32 v139, v139
	v_ashrrev_i32_e32 v163, 31, v162
	v_lshlrev_b64 v[192:193], 6, v[162:163]
	v_add_f32_e32 v137, 1.0, v137
	v_add_f32_e32 v139, 1.0, v139
	v_rcp_f32_e32 v137, v137
	v_rcp_f32_e32 v139, v139
	v_lshl_add_u64 v[168:169], v[168:169], 0, v[192:193]
	global_store_dwordx2 v[168:169], v[190:191], off
	v_fma_f32 v137, v137, s66, 0.5
	v_fma_f32 v139, v139, s66, 0.5
	v_cvt_u32_f32_e32 v137, v137
	v_cvt_u32_f32_e32 v139, v139
	v_lshl_add_u64 v[170:171], v[170:171], 0, s[60:61]
	v_cmp_gt_i32_e64 s[12:13], 2, v186
	s_and_b64 s[80:81], s[82:83], s[12:13]
	v_lshl_or_b32 v137, v139, 8, v137
	v_mul_f32_e32 v139, 0xbfb8aa3b, v114
	v_exp_f32_e32 v139, v139
	s_nop 0
	v_add_f32_e32 v139, 1.0, v139
	v_rcp_f32_e32 v190, v139
	v_mul_f32_e32 v139, 0xbfb8aa3b, v115
	v_exp_f32_e32 v139, v139
	s_nop 0
	v_add_f32_e32 v139, 1.0, v139
	v_rcp_f32_e32 v191, v139
	s_nop 0
	v_pk_fma_f32 v[190:191], v[190:191], s[66:67], 0.5 op_sel_hi:[1,0,0]
	s_nop 0
	v_cvt_u32_f32_sdwa v139, v190 dst_sel:WORD_1 dst_unused:UNUSED_PAD src0_sel:DWORD
	v_cvt_u32_f32_sdwa v163, v191 dst_sel:BYTE_3 dst_unused:UNUSED_PAD src0_sel:DWORD
	v_add_co_u32_e32 v190, vcc, 0x100000, v170
	v_or3_b32 v137, v137, v139, v163
	s_nop 0
	v_addc_co_u32_e32 v191, vcc, 0, v171, vcc
	global_store_dword v[190:191], v137, off
	s_and_saveexec_b64 s[12:13], s[80:81]
	s_cbranch_execz .LBB0_284
	v_lshl_add_u32 v192, s76, 1, v186
	v_ashrrev_i32_e32 v193, 31, v192
	v_readlane_b32 s14, v251, 31
	v_lshlrev_b64 v[192:193], 11, v[192:193]
	v_readlane_b32 s15, v251, 32
	v_cvt_pk_bf16_f32 v190, v124, v125
	v_cvt_pk_bf16_f32 v191, v126, v127
	v_lshl_add_u64 v[192:193], s[14:15], 0, v[192:193]
	v_lshl_add_u64 v[192:193], v[166:167], 1, v[192:193]
	global_store_dwordx2 v[192:193], v[190:191], off
.LBB0_284:
	s_or_b64 exec, exec, s[12:13]
	v_pk_mul_f32 v[192:193], v[104:105], v[100:101]
	v_mov_b32_e32 v195, v132
	s_nop 1
	v_mov_b32_dpp v163, v192 row_ror:1 row_mask:0xf bank_mask:0xf
	v_mov_b32_e32 v194, v192
	v_cndmask_b32_e64 v137, v141, v163, s[8:9]
	v_mov_b32_dpp v167, v192 row_ror:2 row_mask:0xf bank_mask:0xf
	v_pk_mul_f32 v[194:195], v[194:195], v[136:137]
	v_cndmask_b32_e64 v139, v143, v167, s[10:11]
	v_fma_f32 v137, v128, v139, v195
	v_add_f32_e32 v137, v194, v137
	v_mov_b32_dpp v194, v193 row_ror:1 row_mask:0xf bank_mask:0xf
	v_mov_b32_dpp v195, v193 row_ror:2 row_mask:0xf bank_mask:0xf
	v_mov_b32_e32 v192, v193
	v_cndmask_b32_e64 v141, v152, v194, s[8:9]
	v_mov_b32_e32 v193, v133
	v_cndmask_b32_e64 v139, v174, v195, s[10:11]
	v_pk_mul_f32 v[192:193], v[192:193], v[140:141]
	v_pk_mul_f32 v[190:191], v[106:107], v[102:103]
	v_fma_f32 v139, v129, v139, v193
	v_add_f32_e32 v141, v192, v139
	v_mov_b32_dpp v152, v190 row_ror:1 row_mask:0xf bank_mask:0xf
	v_mov_b32_e32 v174, v190
	v_cndmask_b32_e64 v139, v175, v152, s[8:9]
	v_mov_b32_e32 v175, v134
	v_mov_b32_dpp v192, v190 row_ror:2 row_mask:0xf bank_mask:0xf
	v_pk_mul_f32 v[174:175], v[174:175], v[138:139]
	v_cndmask_b32_e64 v143, v187, v192, s[10:11]
	v_fma_f32 v139, v130, v143, v175
	v_add_f32_e32 v139, v174, v139
	v_mov_b32_dpp v187, v191 row_ror:1 row_mask:0xf bank_mask:0xf
	v_mov_b32_e32 v174, v191
	v_cndmask_b32_e64 v143, v188, v187, s[8:9]
	v_mov_b32_e32 v175, v135
	v_mov_b32_dpp v193, v191 row_ror:2 row_mask:0xf bank_mask:0xf
	v_pk_mul_f32 v[174:175], v[174:175], v[142:143]
	v_cndmask_b32_e64 v188, v189, v193, s[10:11]
	v_fma_f32 v143, v131, v188, v175
	v_add_f32_e32 v143, v174, v143
	v_mul_f32_e32 v174, 0xbfb8aa3b, v96
	v_exp_f32_e32 v175, v174
	v_mul_f32_e32 v137, v108, v137
	v_mul_f32_e32 v141, v109, v141
	v_cvt_pk_bf16_f32 v174, v137, v141
	v_mul_f32_e32 v137, v110, v139
	v_add_f32_e32 v139, 1.0, v175
	v_mul_f32_e32 v141, 0xbfb8aa3b, v97
	v_mul_f32_e32 v175, 0xbfb8aa3b, v98
	v_exp_f32_e32 v141, v141
	v_exp_f32_e32 v175, v175
	v_mul_f32_e32 v188, 0xbfb8aa3b, v99
	v_exp_f32_e32 v188, v188
	v_add_f32_e32 v141, 1.0, v141
	v_add_f32_e32 v175, 1.0, v175
	v_rcp_f32_e32 v139, v139
	v_rcp_f32_e32 v141, v141
	v_rcp_f32_e32 v175, v175
	v_add_f32_e32 v188, 1.0, v188
	v_rcp_f32_e32 v188, v188
	v_fma_f32 v139, v139, s66, 0.5
	v_fma_f32 v141, v141, s66, 0.5
	v_fma_f32 v175, v175, s66, 0.5
	v_cvt_u32_f32_e32 v139, v139
	v_cvt_u32_f32_e32 v141, v141
	v_cvt_u32_f32_sdwa v189, v175 dst_sel:WORD_1 dst_unused:UNUSED_PAD src0_sel:DWORD
	v_fma_f32 v175, v188, s66, 0.5
	v_cvt_u32_f32_sdwa v188, v175 dst_sel:BYTE_3 dst_unused:UNUSED_PAD src0_sel:DWORD
	v_mul_f32_e32 v143, v111, v143
	s_mov_b64 s[12:13], 0x100000
	v_cvt_pk_bf16_f32 v175, v137, v143
	v_lshl_or_b32 v137, v141, 8, v139
	v_lshl_add_u64 v[170:171], v[170:171], 0, s[12:13]
	v_or3_b32 v137, v137, v189, v188
	v_pk_mul_f32 v[188:189], v[88:89], v[84:85]
	global_store_dwordx2 v[168:169], v[174:175], off offset:1024
	global_store_dword v[170:171], v137, off offset:1024
	v_mov_b32_dpp v196, v188 row_ror:1 row_mask:0xf bank_mask:0xf
	v_mov_b32_e32 v190, v188
	v_cndmask_b32_e64 v137, v163, v196, s[8:9]
	v_mov_b32_e32 v191, v132
	v_mov_b32_dpp v197, v188 row_ror:2 row_mask:0xf bank_mask:0xf
	v_pk_mul_f32 v[190:191], v[190:191], v[136:137]
	v_cndmask_b32_e64 v139, v167, v197, s[10:11]
	v_mov_b32_dpp v163, v189 row_ror:1 row_mask:0xf bank_mask:0xf
	v_mov_b32_dpp v167, v189 row_ror:2 row_mask:0xf bank_mask:0xf
	v_mov_b32_e32 v188, v189
	v_cndmask_b32_e64 v141, v194, v163, s[8:9]
	v_mov_b32_e32 v189, v133
	v_fma_f32 v137, v128, v139, v191
	v_cndmask_b32_e64 v139, v195, v167, s[10:11]
	v_pk_mul_f32 v[188:189], v[188:189], v[140:141]
	v_pk_mul_f32 v[174:175], v[90:91], v[86:87]
	v_fma_f32 v139, v129, v139, v189
	v_add_f32_e32 v141, v188, v139
	v_mov_b32_dpp v194, v174 row_ror:1 row_mask:0xf bank_mask:0xf
	v_mov_b32_e32 v188, v174
	v_cndmask_b32_e64 v139, v152, v194, s[8:9]
	v_mov_b32_e32 v189, v134
	v_mov_b32_dpp v195, v174 row_ror:2 row_mask:0xf bank_mask:0xf
	v_pk_mul_f32 v[188:189], v[188:189], v[138:139]
	v_cndmask_b32_e64 v143, v192, v195, s[10:11]
	v_fma_f32 v139, v130, v143, v189
	v_mov_b32_dpp v152, v175 row_ror:1 row_mask:0xf bank_mask:0xf
	v_mov_b32_dpp v192, v175 row_ror:2 row_mask:0xf bank_mask:0xf
	v_mov_b32_e32 v174, v175
	v_cndmask_b32_e64 v143, v187, v152, s[8:9]
	v_mov_b32_e32 v175, v135
	v_cndmask_b32_e64 v187, v193, v192, s[10:11]
	v_pk_mul_f32 v[174:175], v[174:175], v[142:143]
	v_add_f32_e32 v137, v190, v137
	v_fma_f32 v143, v131, v187, v175
	v_add_f32_e32 v143, v174, v143
	v_mul_f32_e32 v174, 0xbfb8aa3b, v80
	v_exp_f32_e32 v175, v174
	v_add_f32_e32 v139, v188, v139
	v_mul_f32_e32 v137, v92, v137
	v_mul_f32_e32 v141, v93, v141
	v_cvt_pk_bf16_f32 v174, v137, v141
	v_mul_f32_e32 v137, v94, v139
	v_add_f32_e32 v139, 1.0, v175
	v_mul_f32_e32 v141, 0xbfb8aa3b, v81
	v_mul_f32_e32 v175, 0xbfb8aa3b, v82
	v_exp_f32_e32 v141, v141
	v_exp_f32_e32 v175, v175
	v_mul_f32_e32 v187, 0xbfb8aa3b, v83
	v_exp_f32_e32 v187, v187
	v_add_f32_e32 v141, 1.0, v141
	v_add_f32_e32 v175, 1.0, v175
	v_rcp_f32_e32 v139, v139
	v_rcp_f32_e32 v141, v141
	v_rcp_f32_e32 v175, v175
	v_add_f32_e32 v187, 1.0, v187
	v_rcp_f32_e32 v187, v187
	v_fma_f32 v139, v139, s66, 0.5
	v_fma_f32 v141, v141, s66, 0.5
	v_fma_f32 v175, v175, s66, 0.5
	v_cvt_u32_f32_e32 v139, v139
	v_cvt_u32_f32_e32 v141, v141
	v_cvt_u32_f32_sdwa v188, v175 dst_sel:WORD_1 dst_unused:UNUSED_PAD src0_sel:DWORD
	v_fma_f32 v175, v187, s66, 0.5
	v_cvt_u32_f32_sdwa v187, v175 dst_sel:BYTE_3 dst_unused:UNUSED_PAD src0_sel:DWORD
	v_mul_f32_e32 v143, v95, v143
	v_cvt_pk_bf16_f32 v175, v137, v143
	v_lshl_or_b32 v137, v141, 8, v139
	v_or3_b32 v137, v137, v188, v187
	global_store_dwordx2 v[168:169], v[174:175], off offset:2048
	global_store_dword v[170:171], v137, off offset:2048
	v_pk_mul_f32 v[188:189], v[72:73], v[68:69]
	v_mov_b32_e32 v191, v132
	s_nop 1
	v_mov_b32_dpp v137, v188 row_ror:1 row_mask:0xf bank_mask:0xf
	v_mov_b32_dpp v139, v188 row_ror:2 row_mask:0xf bank_mask:0xf
	v_mov_b32_e32 v190, v188
	v_cndmask_b32_e64 v137, v196, v137, s[8:9]
	v_cndmask_b32_e64 v139, v197, v139, s[10:11]
	v_pk_mul_f32 v[190:191], v[190:191], v[136:137]
	v_mov_b32_e32 v188, v189
	v_fma_f32 v137, v128, v139, v191
	v_mov_b32_dpp v139, v189 row_ror:1 row_mask:0xf bank_mask:0xf
	v_mov_b32_dpp v143, v189 row_ror:2 row_mask:0xf bank_mask:0xf
	v_mov_b32_e32 v189, v133
	v_cndmask_b32_e64 v141, v163, v139, s[8:9]
	v_cndmask_b32_e64 v139, v167, v143, s[10:11]
	v_pk_mul_f32 v[188:189], v[188:189], v[140:141]
	v_pk_mul_f32 v[174:175], v[74:75], v[70:71]
	v_fma_f32 v139, v129, v139, v189
	v_add_f32_e32 v141, v188, v139
	v_mov_b32_dpp v139, v174 row_ror:1 row_mask:0xf bank_mask:0xf
	v_mov_b32_dpp v143, v174 row_ror:2 row_mask:0xf bank_mask:0xf
	v_mov_b32_e32 v188, v174
	v_cndmask_b32_e64 v139, v194, v139, s[8:9]
	v_mov_b32_e32 v189, v134
	v_cndmask_b32_e64 v143, v195, v143, s[10:11]
	v_pk_mul_f32 v[188:189], v[188:189], v[138:139]
	v_mov_b32_e32 v174, v175
	v_fma_f32 v139, v130, v143, v189
	v_mov_b32_dpp v143, v175 row_ror:1 row_mask:0xf bank_mask:0xf
	v_mov_b32_dpp v163, v175 row_ror:2 row_mask:0xf bank_mask:0xf
	v_mov_b32_e32 v175, v135
	v_cndmask_b32_e64 v143, v152, v143, s[8:9]
	v_cndmask_b32_e64 v152, v192, v163, s[10:11]
	v_pk_mul_f32 v[174:175], v[174:175], v[142:143]
	v_add_f32_e32 v137, v190, v137
	v_fma_f32 v143, v131, v152, v175
	v_mul_f32_e32 v152, 0xbfb8aa3b, v64
	v_exp_f32_e32 v152, v152
	v_add_f32_e32 v139, v188, v139
	v_add_f32_e32 v143, v174, v143
	v_mul_f32_e32 v137, v76, v137
	v_mul_f32_e32 v141, v77, v141
	v_cvt_pk_bf16_f32 v188, v137, v141
	v_mul_f32_e32 v137, v78, v139
	v_mul_f32_e32 v139, v79, v143
	v_add_f32_e32 v141, 1.0, v152
	v_mul_f32_e32 v143, 0xbfb8aa3b, v65
	v_rcp_f32_e32 v141, v141
	v_exp_f32_e32 v143, v143
	v_cvt_pk_bf16_f32 v189, v137, v139
	s_add_i32 s12, 0, 0x22600
	v_fma_f32 v137, v141, s66, 0.5
	v_add_f32_e32 v139, 1.0, v143
	v_mul_f32_e32 v141, 0xbfb8aa3b, v66
	v_mul_f32_e32 v143, 0xbfb8aa3b, v67
	v_exp_f32_e32 v141, v141
	v_exp_f32_e32 v143, v143
	v_rcp_f32_e32 v139, v139
	v_cvt_u32_f32_e32 v137, v137
	v_add_f32_e32 v141, 1.0, v141
	v_add_f32_e32 v143, 1.0, v143
	v_rcp_f32_e32 v141, v141
	v_rcp_f32_e32 v143, v143
	v_fma_f32 v139, v139, s66, 0.5
	v_cvt_u32_f32_e32 v139, v139
	v_fma_f32 v141, v141, s66, 0.5
	v_fma_f32 v143, v143, s66, 0.5
	v_cvt_u32_f32_sdwa v141, v141 dst_sel:WORD_1 dst_unused:UNUSED_PAD src0_sel:DWORD
	v_cvt_u32_f32_sdwa v143, v143 dst_sel:BYTE_3 dst_unused:UNUSED_PAD src0_sel:DWORD
	v_add3_u32 v152, s12, v165, v173
	s_movk_i32 s12, 0x400
	v_add3_u32 v163, v172, v173, s12
	v_cndmask_b32_e64 v152, v163, v152, s[0:1]
	v_lshl_add_u32 v152, v185, 4, v152
	v_lshl_or_b32 v137, v139, 8, v137
	ds_read_b128 v[172:175], v152
	v_or3_b32 v137, v137, v141, v143
	global_store_dwordx2 v[168:169], v[188:189], off offset:3072
	global_store_dword v[170:171], v137, off offset:3072
	s_waitcnt lgkmcnt(0)
	v_mov_b32_dpp v137, v172 row_ror:1 row_mask:0xf bank_mask:0xf
	v_mov_b32_dpp v139, v172 row_ror:2 row_mask:0xf bank_mask:0xf
	v_mov_b32_dpp v141, v173 row_ror:1 row_mask:0xf bank_mask:0xf
	v_mov_b32_dpp v143, v173 row_ror:2 row_mask:0xf bank_mask:0xf
	v_mov_b32_dpp v152, v174 row_ror:1 row_mask:0xf bank_mask:0xf
	v_mov_b32_dpp v163, v174 row_ror:2 row_mask:0xf bank_mask:0xf
	v_mov_b32_dpp v165, v175 row_ror:1 row_mask:0xf bank_mask:0xf
	v_mov_b32_dpp v167, v175 row_ror:2 row_mask:0xf bank_mask:0xf
	v_pk_mul_f32 v[174:175], v[56:57], v[52:53]
	v_mov_b32_e32 v189, v132
	s_nop 1
	v_mov_b32_dpp v187, v174 row_ror:1 row_mask:0xf bank_mask:0xf
	v_mov_b32_e32 v188, v174
	v_cndmask_b32_e64 v137, v137, v187, s[8:9]
	v_mov_b32_dpp v190, v174 row_ror:2 row_mask:0xf bank_mask:0xf
	v_pk_mul_f32 v[188:189], v[188:189], v[136:137]
	v_cndmask_b32_e64 v139, v139, v190, s[10:11]
	v_mov_b32_dpp v191, v175 row_ror:1 row_mask:0xf bank_mask:0xf
	v_mov_b32_dpp v192, v175 row_ror:2 row_mask:0xf bank_mask:0xf
	v_mov_b32_e32 v174, v175
	v_cndmask_b32_e64 v141, v141, v191, s[8:9]
	v_mov_b32_e32 v175, v133
	v_fma_f32 v137, v128, v139, v189
	v_cndmask_b32_e64 v139, v143, v192, s[10:11]
	v_pk_mul_f32 v[174:175], v[174:175], v[140:141]
	v_pk_mul_f32 v[172:173], v[58:59], v[54:55]
	v_fma_f32 v139, v129, v139, v175
	v_add_f32_e32 v141, v174, v139
	v_mov_b32_dpp v193, v172 row_ror:1 row_mask:0xf bank_mask:0xf
	v_mov_b32_e32 v174, v172
	v_cndmask_b32_e64 v139, v152, v193, s[8:9]
	v_mov_b32_e32 v175, v134
	v_mov_b32_dpp v194, v172 row_ror:2 row_mask:0xf bank_mask:0xf
	v_pk_mul_f32 v[174:175], v[174:175], v[138:139]
	v_cndmask_b32_e64 v143, v163, v194, s[10:11]
	v_fma_f32 v139, v130, v143, v175
	v_mov_b32_dpp v152, v173 row_ror:1 row_mask:0xf bank_mask:0xf
	v_mov_b32_dpp v163, v173 row_ror:2 row_mask:0xf bank_mask:0xf
	v_mov_b32_e32 v172, v173
	v_cndmask_b32_e64 v143, v165, v152, s[8:9]
	v_mov_b32_e32 v173, v135
	v_cndmask_b32_e64 v165, v167, v163, s[10:11]
	v_pk_mul_f32 v[172:173], v[172:173], v[142:143]
	v_add_f32_e32 v137, v188, v137
	v_fma_f32 v143, v131, v165, v173
	v_mul_f32_e32 v165, 0xbfb8aa3b, v48
	v_exp_f32_e32 v165, v165
	v_add_f32_e32 v139, v174, v139
	v_add_f32_e32 v143, v172, v143
	v_mul_f32_e32 v137, v60, v137
	v_mul_f32_e32 v141, v61, v141
	v_cvt_pk_bf16_f32 v172, v137, v141
	v_mul_f32_e32 v137, v62, v139
	v_mul_f32_e32 v139, v63, v143
	v_add_f32_e32 v141, 1.0, v165
	v_mul_f32_e32 v143, 0xbfb8aa3b, v49
	v_rcp_f32_e32 v141, v141
	v_exp_f32_e32 v143, v143
	v_cvt_pk_bf16_f32 v173, v137, v139
	s_movk_i32 s12, 0x2000
	v_fma_f32 v137, v141, s66, 0.5
	v_add_f32_e32 v139, 1.0, v143
	v_mul_f32_e32 v141, 0xbfb8aa3b, v50
	v_mul_f32_e32 v143, 0xbfb8aa3b, v51
	v_exp_f32_e32 v141, v141
	v_exp_f32_e32 v143, v143
	v_rcp_f32_e32 v139, v139
	v_cvt_u32_f32_e32 v137, v137
	v_add_f32_e32 v141, 1.0, v141
	v_add_f32_e32 v143, 1.0, v143
	v_rcp_f32_e32 v141, v141
	v_rcp_f32_e32 v143, v143
	v_fma_f32 v139, v139, s66, 0.5
	v_cvt_u32_f32_e32 v139, v139
	v_fma_f32 v141, v141, s66, 0.5
	v_fma_f32 v143, v143, s66, 0.5
	v_cvt_u32_f32_sdwa v141, v141 dst_sel:WORD_1 dst_unused:UNUSED_PAD src0_sel:DWORD
	v_cvt_u32_f32_sdwa v143, v143 dst_sel:BYTE_3 dst_unused:UNUSED_PAD src0_sel:DWORD
	v_add_co_u32_e32 v168, vcc, s12, v168
	s_movk_i32 s12, 0x1000
	s_nop 0
	v_addc_co_u32_e32 v169, vcc, 0, v169, vcc
	v_lshl_or_b32 v137, v139, 8, v137
	v_add_co_u32_e32 v170, vcc, s12, v170
	v_or3_b32 v137, v137, v141, v143
	s_nop 0
	v_addc_co_u32_e32 v171, vcc, 0, v171, vcc
	v_pk_mul_f32 v[174:175], v[40:41], v[36:37]
	global_store_dwordx2 v[168:169], v[172:173], off
	global_store_dword v[170:171], v137, off
	v_mov_b32_dpp v165, v174 row_ror:1 row_mask:0xf bank_mask:0xf
	v_mov_b32_e32 v188, v174
	v_cndmask_b32_e64 v137, v187, v165, s[8:9]
	v_mov_b32_e32 v189, v132
	v_mov_b32_dpp v167, v174 row_ror:2 row_mask:0xf bank_mask:0xf
	v_pk_mul_f32 v[188:189], v[188:189], v[136:137]
	v_cndmask_b32_e64 v139, v190, v167, s[10:11]
	v_mov_b32_dpp v187, v175 row_ror:1 row_mask:0xf bank_mask:0xf
	v_mov_b32_dpp v190, v175 row_ror:2 row_mask:0xf bank_mask:0xf
	v_mov_b32_e32 v174, v175
	v_cndmask_b32_e64 v141, v191, v187, s[8:9]
	v_mov_b32_e32 v175, v133
	v_fma_f32 v137, v128, v139, v189
	v_cndmask_b32_e64 v139, v192, v190, s[10:11]
	v_pk_mul_f32 v[174:175], v[174:175], v[140:141]
	v_pk_mul_f32 v[172:173], v[42:43], v[38:39]
	v_fma_f32 v139, v129, v139, v175
	v_add_f32_e32 v141, v174, v139
	v_mov_b32_dpp v191, v172 row_ror:1 row_mask:0xf bank_mask:0xf
	v_mov_b32_e32 v174, v172
	v_cndmask_b32_e64 v139, v193, v191, s[8:9]
	v_mov_b32_e32 v175, v134
	v_mov_b32_dpp v192, v172 row_ror:2 row_mask:0xf bank_mask:0xf
	v_pk_mul_f32 v[174:175], v[174:175], v[138:139]
	v_cndmask_b32_e64 v143, v194, v192, s[10:11]
	v_fma_f32 v139, v130, v143, v175
	v_mov_b32_dpp v193, v173 row_ror:1 row_mask:0xf bank_mask:0xf
	v_mov_b32_dpp v194, v173 row_ror:2 row_mask:0xf bank_mask:0xf
	v_mov_b32_e32 v172, v173
	v_cndmask_b32_e64 v143, v152, v193, s[8:9]
	v_mov_b32_e32 v173, v135
	v_cndmask_b32_e64 v152, v163, v194, s[10:11]
	v_pk_mul_f32 v[172:173], v[172:173], v[142:143]
	v_add_f32_e32 v137, v188, v137
	v_fma_f32 v143, v131, v152, v173
	v_mul_f32_e32 v152, 0xbfb8aa3b, v32
	v_exp_f32_e32 v152, v152
	v_mul_f32_e32 v137, v44, v137
	v_mul_f32_e32 v141, v45, v141
	v_add_f32_e32 v139, v174, v139
	v_add_f32_e32 v143, v172, v143
	v_cvt_pk_bf16_f32 v172, v137, v141
	v_mul_f32_e32 v141, 0xbfb8aa3b, v33
	v_mul_f32_e32 v137, v46, v139
	v_add_f32_e32 v139, 1.0, v152
	v_exp_f32_e32 v141, v141
	v_mul_f32_e32 v152, 0xbfb8aa3b, v34
	v_mul_f32_e32 v163, 0xbfb8aa3b, v35
	v_exp_f32_e32 v152, v152
	v_exp_f32_e32 v163, v163
	v_add_f32_e32 v141, 1.0, v141
	v_rcp_f32_e32 v139, v139
	v_rcp_f32_e32 v141, v141
	v_add_f32_e32 v152, 1.0, v152
	v_add_f32_e32 v163, 1.0, v163
	v_rcp_f32_e32 v152, v152
	v_rcp_f32_e32 v163, v163
	v_fma_f32 v139, v139, s66, 0.5
	v_fma_f32 v141, v141, s66, 0.5
	v_cvt_u32_f32_e32 v139, v139
	v_cvt_u32_f32_e32 v141, v141
	v_fma_f32 v152, v152, s66, 0.5
	v_fma_f32 v163, v163, s66, 0.5
	v_cvt_u32_f32_sdwa v152, v152 dst_sel:WORD_1 dst_unused:UNUSED_PAD src0_sel:DWORD
	v_cvt_u32_f32_sdwa v163, v163 dst_sel:BYTE_3 dst_unused:UNUSED_PAD src0_sel:DWORD
	v_mul_f32_e32 v143, v47, v143
	v_cvt_pk_bf16_f32 v173, v137, v143
	v_lshl_or_b32 v137, v141, 8, v139
	v_or3_b32 v137, v137, v152, v163
	v_pk_mul_f32 v[174:175], v[24:25], v[20:21]
	global_store_dwordx2 v[168:169], v[172:173], off offset:1024
	global_store_dword v[170:171], v137, off offset:1024
	v_mov_b32_dpp v152, v174 row_ror:1 row_mask:0xf bank_mask:0xf
	v_mov_b32_e32 v188, v174
	v_cndmask_b32_e64 v137, v165, v152, s[8:9]
	v_mov_b32_e32 v189, v132
	v_mov_b32_dpp v163, v174 row_ror:2 row_mask:0xf bank_mask:0xf
	v_pk_mul_f32 v[188:189], v[188:189], v[136:137]
	v_cndmask_b32_e64 v139, v167, v163, s[10:11]
	v_mov_b32_dpp v165, v175 row_ror:1 row_mask:0xf bank_mask:0xf
	v_mov_b32_dpp v167, v175 row_ror:2 row_mask:0xf bank_mask:0xf
	v_mov_b32_e32 v174, v175
	v_cndmask_b32_e64 v141, v187, v165, s[8:9]
	v_mov_b32_e32 v175, v133
	v_fma_f32 v137, v128, v139, v189
	v_cndmask_b32_e64 v139, v190, v167, s[10:11]
	v_pk_mul_f32 v[174:175], v[174:175], v[140:141]
	v_pk_mul_f32 v[172:173], v[26:27], v[22:23]
	v_fma_f32 v139, v129, v139, v175
	v_add_f32_e32 v141, v174, v139
	v_mov_b32_dpp v187, v172 row_ror:1 row_mask:0xf bank_mask:0xf
	v_mov_b32_e32 v174, v172
	v_cndmask_b32_e64 v139, v191, v187, s[8:9]
	v_mov_b32_e32 v175, v134
	v_mov_b32_dpp v190, v172 row_ror:2 row_mask:0xf bank_mask:0xf
	v_pk_mul_f32 v[174:175], v[174:175], v[138:139]
	v_cndmask_b32_e64 v143, v192, v190, s[10:11]
	v_fma_f32 v139, v130, v143, v175
	v_mov_b32_dpp v191, v173 row_ror:1 row_mask:0xf bank_mask:0xf
	v_mov_b32_dpp v192, v173 row_ror:2 row_mask:0xf bank_mask:0xf
	v_mov_b32_e32 v172, v173
	v_cndmask_b32_e64 v143, v193, v191, s[8:9]
	v_mov_b32_e32 v173, v135
	v_add_f32_e32 v139, v174, v139
	v_cndmask_b32_e64 v174, v194, v192, s[10:11]
	v_pk_mul_f32 v[172:173], v[172:173], v[142:143]
	v_add_f32_e32 v137, v188, v137
	v_fma_f32 v143, v131, v174, v173
	v_add_f32_e32 v143, v172, v143
	v_mul_f32_e32 v172, 0xbfb8aa3b, v16
	v_exp_f32_e32 v173, v172
	v_mul_f32_e32 v137, v28, v137
	v_mul_f32_e32 v141, v29, v141
	v_cvt_pk_bf16_f32 v172, v137, v141
	v_mul_f32_e32 v137, v30, v139
	v_add_f32_e32 v139, 1.0, v173
	v_mul_f32_e32 v141, 0xbfb8aa3b, v17
	v_mul_f32_e32 v173, 0xbfb8aa3b, v18
	v_exp_f32_e32 v141, v141
	v_exp_f32_e32 v173, v173
	v_mul_f32_e32 v174, 0xbfb8aa3b, v19
	v_exp_f32_e32 v174, v174
	v_add_f32_e32 v141, 1.0, v141
	v_add_f32_e32 v173, 1.0, v173
	v_rcp_f32_e32 v139, v139
	v_rcp_f32_e32 v141, v141
	v_rcp_f32_e32 v173, v173
	v_add_f32_e32 v174, 1.0, v174
	v_rcp_f32_e32 v174, v174
	v_fma_f32 v139, v139, s66, 0.5
	v_fma_f32 v141, v141, s66, 0.5
	v_fma_f32 v173, v173, s66, 0.5
	v_cvt_u32_f32_e32 v139, v139
	v_cvt_u32_f32_e32 v141, v141
	v_cvt_u32_f32_sdwa v175, v173 dst_sel:WORD_1 dst_unused:UNUSED_PAD src0_sel:DWORD
	v_fma_f32 v173, v174, s66, 0.5
	v_cvt_u32_f32_sdwa v174, v173 dst_sel:BYTE_3 dst_unused:UNUSED_PAD src0_sel:DWORD
	v_mul_f32_e32 v143, v31, v143
	v_cvt_pk_bf16_f32 v173, v137, v143
	v_lshl_or_b32 v137, v141, 8, v139
	v_or3_b32 v137, v137, v175, v174
	global_store_dwordx2 v[168:169], v[172:173], off offset:2048
	global_store_dword v[170:171], v137, off offset:2048
	v_pk_mul_f32 v[174:175], v[8:9], v[4:5]
	v_mov_b32_e32 v189, v132
	s_nop 1
	v_mov_b32_dpp v137, v174 row_ror:1 row_mask:0xf bank_mask:0xf
	v_mov_b32_dpp v139, v174 row_ror:2 row_mask:0xf bank_mask:0xf
	v_mov_b32_e32 v188, v174
	v_cndmask_b32_e64 v137, v152, v137, s[8:9]
	v_cndmask_b32_e64 v139, v163, v139, s[10:11]
	v_pk_mul_f32 v[136:137], v[188:189], v[136:137]
	v_pk_mul_f32 v[172:173], v[10:11], v[6:7]
	v_fma_f32 v128, v128, v139, v137
	v_add_f32_e32 v136, v136, v128
	v_mov_b32_dpp v128, v175 row_ror:1 row_mask:0xf bank_mask:0xf
	v_mov_b32_dpp v132, v175 row_ror:2 row_mask:0xf bank_mask:0xf
	s_nop 0
	v_cndmask_b32_e64 v141, v165, v128, s[8:9]
	v_cndmask_b32_e64 v128, v167, v132, s[10:11]
	v_mov_b32_e32 v132, v175
	v_pk_mul_f32 v[132:133], v[132:133], v[140:141]
	s_nop 0
	v_fma_f32 v128, v129, v128, v133
	v_add_f32_e32 v132, v132, v128
	v_mov_b32_dpp v128, v172 row_ror:1 row_mask:0xf bank_mask:0xf
	v_mov_b32_dpp v129, v172 row_ror:2 row_mask:0xf bank_mask:0xf
	v_mul_f32_e32 v132, v13, v132
	v_cndmask_b32_e64 v139, v187, v128, s[8:9]
	v_cndmask_b32_e64 v133, v190, v129, s[10:11]
	v_mov_b32_e32 v128, v172
	v_mov_b32_e32 v129, v134
	v_pk_mul_f32 v[128:129], v[128:129], v[138:139]
	v_mov_b32_e32 v134, v173
	v_fma_f32 v129, v130, v133, v129
	v_add_f32_e32 v130, v128, v129
	v_mov_b32_dpp v128, v173 row_ror:1 row_mask:0xf bank_mask:0xf
	v_mov_b32_dpp v129, v173 row_ror:2 row_mask:0xf bank_mask:0xf
	v_mul_f32_e32 v130, v14, v130
	v_cndmask_b32_e64 v143, v191, v128, s[8:9]
	v_cndmask_b32_e64 v133, v192, v129, s[10:11]
	v_pk_mul_f32 v[128:129], v[134:135], v[142:143]
	v_mul_f32_e32 v134, 0xbfb8aa3b, v3
	v_fma_f32 v129, v131, v133, v129
	v_add_f32_e32 v129, v128, v129
	v_mul_f32_e32 v128, v12, v136
	v_mul_f32_e32 v131, 0xbfb8aa3b, v0
	v_cvt_pk_bf16_f32 v128, v128, v132
	v_mul_f32_e32 v132, 0xbfb8aa3b, v1
	v_exp_f32_e32 v131, v131
	v_exp_f32_e32 v132, v132
	v_mul_f32_e32 v133, 0xbfb8aa3b, v2
	v_exp_f32_e32 v133, v133
	v_exp_f32_e32 v134, v134
	v_add_f32_e32 v131, 1.0, v131
	v_add_f32_e32 v132, 1.0, v132
	v_rcp_f32_e32 v131, v131
	v_rcp_f32_e32 v132, v132
	v_add_f32_e32 v133, 1.0, v133
	v_add_f32_e32 v134, 1.0, v134
	v_rcp_f32_e32 v133, v133
	v_rcp_f32_e32 v134, v134
	v_fma_f32 v131, v131, s66, 0.5
	v_fma_f32 v132, v132, s66, 0.5
	v_cvt_u32_f32_e32 v131, v131
	v_cvt_u32_f32_e32 v132, v132
	v_fma_f32 v133, v133, s66, 0.5
	v_fma_f32 v134, v134, s66, 0.5
	v_cvt_u32_f32_sdwa v133, v133 dst_sel:WORD_1 dst_unused:UNUSED_PAD src0_sel:DWORD
	v_cvt_u32_f32_sdwa v134, v134 dst_sel:BYTE_3 dst_unused:UNUSED_PAD src0_sel:DWORD
	v_mul_f32_e32 v129, v15, v129
	v_cvt_pk_bf16_f32 v129, v130, v129
	global_store_dwordx2 v[168:169], v[128:129], off offset:3072
	v_lshl_or_b32 v128, v132, 8, v131
	v_or3_b32 v128, v128, v133, v134
	s_and_b64 s[8:9], s[0:1], s[6:7]
	global_store_dword v[170:171], v128, off offset:3072
	s_and_saveexec_b64 s[6:7], s[8:9]
	s_cbranch_execz .LBB0_286
	s_lshl_b32 s8, s76, 12
	v_lshlrev_b32_e32 v130, 11, v186
	v_lshlrev_b32_e32 v131, 1, v166
	s_addk_i32 s8, 0x9000
	v_cvt_pk_bf16_f32 v128, v174, v175
	v_cvt_pk_bf16_f32 v129, v172, v173
	v_add3_u32 v130, s8, v130, v131
	buffer_store_dwordx2 v[128:129], v130, s[28:31], 0 offen sc1
